# stack25 + P5 per-head scan prologue unrolled with gate loads kept four iterations ahead (was 32 dependent global round trips on 4 lanes)
# speedup vs baseline: 1.0139x; 1.0093x over previous
.LBB0_595:
	v_add_u32_e32 v2, 0, v4
	v_ashrrev_i32_e32 v3, 31, v2
	v_lshl_add_u64 v[104:105], v[2:3], 2, s[4:5]
	global_load_dword v64, v[104:105], off
	global_load_dword v65, v[104:105], off offset:2048
	global_load_dword v66, v[104:105], off offset:16
	global_load_dword v67, v[104:105], off offset:32
	global_load_dword v68, v[104:105], off offset:48
	global_load_dword v69, v[104:105], off offset:2064
	global_load_dword v70, v[104:105], off offset:2080
	global_load_dword v71, v[104:105], off offset:2096
	global_load_dword v72, v[104:105], off offset:64
	global_load_dword v73, v[104:105], off offset:2112
	global_load_dword v74, v[104:105], off offset:80
	global_load_dword v75, v[104:105], off offset:96
	global_load_dword v76, v[104:105], off offset:112
	global_load_dword v77, v[104:105], off offset:2128
	global_load_dword v78, v[104:105], off offset:2144
	global_load_dword v79, v[104:105], off offset:2160
	global_load_dword v80, v[104:105], off offset:128
	global_load_dword v81, v[104:105], off offset:2176
	global_load_dword v82, v[104:105], off offset:144
	global_load_dword v83, v[104:105], off offset:160
	global_load_dword v84, v[104:105], off offset:176
	global_load_dword v85, v[104:105], off offset:2192
	global_load_dword v86, v[104:105], off offset:2208
	global_load_dword v87, v[104:105], off offset:2224
	global_load_dword v88, v[104:105], off offset:192
	global_load_dword v89, v[104:105], off offset:2240
	global_load_dword v90, v[104:105], off offset:208
	global_load_dword v91, v[104:105], off offset:224
	global_load_dword v92, v[104:105], off offset:240
	global_load_dword v93, v[104:105], off offset:2256
	global_load_dword v94, v[104:105], off offset:2272
	global_load_dword v95, v[104:105], off offset:2288
	global_load_dword v96, v[104:105], off offset:256
	global_load_dword v97, v[104:105], off offset:2304
	global_load_dword v98, v[104:105], off offset:272
	global_load_dword v99, v[104:105], off offset:288
	global_load_dword v100, v[104:105], off offset:304
	global_load_dword v101, v[104:105], off offset:2320
	global_load_dword v102, v[104:105], off offset:2336
	global_load_dword v103, v[104:105], off offset:2352
	s_waitcnt vmcnt(32)
	v_mov_b32_e32 v12, v64
	v_mov_b32_e32 v1, v65
	v_mov_b32_e32 v11, v66
	v_mov_b32_e32 v13, v67
	v_mov_b32_e32 v14, v68
	v_mov_b32_e32 v10, v69
	v_mov_b32_e32 v15, v70
	v_mov_b32_e32 v16, v71
	v_add_f32_e32 v2, v0, v1
	v_max_f32_e32 v1, v12, v12
	v_max_f32_e32 v1, v2, v1
	v_max_f32_e32 v3, v11, v11
	v_sub_f32_e32 v2, v2, v1
	v_sub_f32_e32 v6, v12, v1
	v_add_f32_e32 v9, v1, v10
	v_mul_f32_e32 v10, 0x3fb8aa3b, v2
	v_mul_f32_e32 v12, 0x3fb8aa3b, v6
	v_max_f32_e32 v2, v9, v3
	v_max_f32_e32 v7, v13, v13
	v_exp_f32_e32 v6, v10
	v_exp_f32_e32 v10, v12
	v_sub_f32_e32 v3, v9, v2
	v_sub_f32_e32 v9, v11, v2
	v_add_f32_e32 v12, v2, v15
	v_mul_f32_e32 v11, 0x3fb8aa3b, v3
	v_mul_f32_e32 v9, 0x3fb8aa3b, v9
	v_max_f32_e32 v3, v12, v7
	v_max_f32_e32 v8, v14, v14
	v_exp_f32_e32 v7, v11
	v_exp_f32_e32 v11, v9
	v_sub_f32_e32 v9, v12, v3
	v_sub_f32_e32 v12, v13, v3
	v_add_f32_e32 v13, v3, v16
	v_mul_f32_e32 v9, 0x3fb8aa3b, v9
	v_max_f32_e32 v15, v13, v8
	v_exp_f32_e32 v8, v9
	v_sub_f32_e32 v9, v13, v15
	v_sub_f32_e32 v13, v14, v15
	v_mul_f32_e32 v9, 0x3fb8aa3b, v9
	v_mul_f32_e32 v12, 0x3fb8aa3b, v12
	v_mul_f32_e32 v13, 0x3fb8aa3b, v13
	v_exp_f32_e32 v9, v9
	v_exp_f32_e32 v12, v12
	v_exp_f32_e32 v13, v13
	ds_write_b128 v5, v[0:3] offset:4096
	v_mov_b32_e32 v0, v15
	ds_write_b128 v5, v[6:9]
	ds_write_b128 v5, v[10:13] offset:2048
	global_load_dword v64, v[104:105], off offset:320
	global_load_dword v65, v[104:105], off offset:2368
	global_load_dword v66, v[104:105], off offset:336
	global_load_dword v67, v[104:105], off offset:352
	global_load_dword v68, v[104:105], off offset:368
	global_load_dword v69, v[104:105], off offset:2384
	global_load_dword v70, v[104:105], off offset:2400
	global_load_dword v71, v[104:105], off offset:2416
	s_waitcnt vmcnt(32)
	v_mov_b32_e32 v12, v72
	v_mov_b32_e32 v1, v73
	v_mov_b32_e32 v11, v74
	v_mov_b32_e32 v13, v75
	v_mov_b32_e32 v14, v76
	v_mov_b32_e32 v10, v77
	v_mov_b32_e32 v15, v78
	v_mov_b32_e32 v16, v79
	v_add_f32_e32 v2, v0, v1
	v_max_f32_e32 v1, v12, v12
	v_max_f32_e32 v1, v2, v1
	v_max_f32_e32 v3, v11, v11
	v_sub_f32_e32 v2, v2, v1
	v_sub_f32_e32 v6, v12, v1
	v_add_f32_e32 v9, v1, v10
	v_mul_f32_e32 v10, 0x3fb8aa3b, v2
	v_mul_f32_e32 v12, 0x3fb8aa3b, v6
	v_max_f32_e32 v2, v9, v3
	v_max_f32_e32 v7, v13, v13
	v_exp_f32_e32 v6, v10
	v_exp_f32_e32 v10, v12
	v_sub_f32_e32 v3, v9, v2
	v_sub_f32_e32 v9, v11, v2
	v_add_f32_e32 v12, v2, v15
	v_mul_f32_e32 v11, 0x3fb8aa3b, v3
	v_mul_f32_e32 v9, 0x3fb8aa3b, v9
	v_max_f32_e32 v3, v12, v7
	v_max_f32_e32 v8, v14, v14
	v_exp_f32_e32 v7, v11
	v_exp_f32_e32 v11, v9
	v_sub_f32_e32 v9, v12, v3
	v_sub_f32_e32 v12, v13, v3
	v_add_f32_e32 v13, v3, v16
	v_mul_f32_e32 v9, 0x3fb8aa3b, v9
	v_max_f32_e32 v15, v13, v8
	v_exp_f32_e32 v8, v9
	v_sub_f32_e32 v9, v13, v15
	v_sub_f32_e32 v13, v14, v15
	v_mul_f32_e32 v9, 0x3fb8aa3b, v9
	v_mul_f32_e32 v12, 0x3fb8aa3b, v12
	v_mul_f32_e32 v13, 0x3fb8aa3b, v13
	v_exp_f32_e32 v9, v9
	v_exp_f32_e32 v12, v12
	v_exp_f32_e32 v13, v13
	ds_write_b128 v5, v[0:3] offset:4112
	v_mov_b32_e32 v0, v15
	ds_write_b128 v5, v[6:9] offset:16
	ds_write_b128 v5, v[10:13] offset:2064
	global_load_dword v72, v[104:105], off offset:384
	global_load_dword v73, v[104:105], off offset:2432
	global_load_dword v74, v[104:105], off offset:400
	global_load_dword v75, v[104:105], off offset:416
	global_load_dword v76, v[104:105], off offset:432
	global_load_dword v77, v[104:105], off offset:2448
	global_load_dword v78, v[104:105], off offset:2464
	global_load_dword v79, v[104:105], off offset:2480
	s_waitcnt vmcnt(32)
	v_mov_b32_e32 v12, v80
	v_mov_b32_e32 v1, v81
	v_mov_b32_e32 v11, v82
	v_mov_b32_e32 v13, v83
	v_mov_b32_e32 v14, v84
	v_mov_b32_e32 v10, v85
	v_mov_b32_e32 v15, v86
	v_mov_b32_e32 v16, v87
	v_add_f32_e32 v2, v0, v1
	v_max_f32_e32 v1, v12, v12
	v_max_f32_e32 v1, v2, v1
	v_max_f32_e32 v3, v11, v11
	v_sub_f32_e32 v2, v2, v1
	v_sub_f32_e32 v6, v12, v1
	v_add_f32_e32 v9, v1, v10
	v_mul_f32_e32 v10, 0x3fb8aa3b, v2
	v_mul_f32_e32 v12, 0x3fb8aa3b, v6
	v_max_f32_e32 v2, v9, v3
	v_max_f32_e32 v7, v13, v13
	v_exp_f32_e32 v6, v10
	v_exp_f32_e32 v10, v12
	v_sub_f32_e32 v3, v9, v2
	v_sub_f32_e32 v9, v11, v2
	v_add_f32_e32 v12, v2, v15
	v_mul_f32_e32 v11, 0x3fb8aa3b, v3
	v_mul_f32_e32 v9, 0x3fb8aa3b, v9
	v_max_f32_e32 v3, v12, v7
	v_max_f32_e32 v8, v14, v14
	v_exp_f32_e32 v7, v11
	v_exp_f32_e32 v11, v9
	v_sub_f32_e32 v9, v12, v3
	v_sub_f32_e32 v12, v13, v3
	v_add_f32_e32 v13, v3, v16
	v_mul_f32_e32 v9, 0x3fb8aa3b, v9
	v_max_f32_e32 v15, v13, v8
	v_exp_f32_e32 v8, v9
	v_sub_f32_e32 v9, v13, v15
	v_sub_f32_e32 v13, v14, v15
	v_mul_f32_e32 v9, 0x3fb8aa3b, v9
	v_mul_f32_e32 v12, 0x3fb8aa3b, v12
	v_mul_f32_e32 v13, 0x3fb8aa3b, v13
	v_exp_f32_e32 v9, v9
	v_exp_f32_e32 v12, v12
	v_exp_f32_e32 v13, v13
	ds_write_b128 v5, v[0:3] offset:4128
	v_mov_b32_e32 v0, v15
	ds_write_b128 v5, v[6:9] offset:32
	ds_write_b128 v5, v[10:13] offset:2080
	global_load_dword v80, v[104:105], off offset:448
	global_load_dword v81, v[104:105], off offset:2496
	global_load_dword v82, v[104:105], off offset:464
	global_load_dword v83, v[104:105], off offset:480
	global_load_dword v84, v[104:105], off offset:496
	global_load_dword v85, v[104:105], off offset:2512
	global_load_dword v86, v[104:105], off offset:2528
	global_load_dword v87, v[104:105], off offset:2544
	s_waitcnt vmcnt(32)
	v_mov_b32_e32 v12, v88
	v_mov_b32_e32 v1, v89
	v_mov_b32_e32 v11, v90
	v_mov_b32_e32 v13, v91
	v_mov_b32_e32 v14, v92
	v_mov_b32_e32 v10, v93
	v_mov_b32_e32 v15, v94
	v_mov_b32_e32 v16, v95
	v_add_f32_e32 v2, v0, v1
	v_max_f32_e32 v1, v12, v12
	v_max_f32_e32 v1, v2, v1
	v_max_f32_e32 v3, v11, v11
	v_sub_f32_e32 v2, v2, v1
	v_sub_f32_e32 v6, v12, v1
	v_add_f32_e32 v9, v1, v10
	v_mul_f32_e32 v10, 0x3fb8aa3b, v2
	v_mul_f32_e32 v12, 0x3fb8aa3b, v6
	v_max_f32_e32 v2, v9, v3
	v_max_f32_e32 v7, v13, v13
	v_exp_f32_e32 v6, v10
	v_exp_f32_e32 v10, v12
	v_sub_f32_e32 v3, v9, v2
	v_sub_f32_e32 v9, v11, v2
	v_add_f32_e32 v12, v2, v15
	v_mul_f32_e32 v11, 0x3fb8aa3b, v3
	v_mul_f32_e32 v9, 0x3fb8aa3b, v9
	v_max_f32_e32 v3, v12, v7
	v_max_f32_e32 v8, v14, v14
	v_exp_f32_e32 v7, v11
	v_exp_f32_e32 v11, v9
	v_sub_f32_e32 v9, v12, v3
	v_sub_f32_e32 v12, v13, v3
	v_add_f32_e32 v13, v3, v16
	v_mul_f32_e32 v9, 0x3fb8aa3b, v9
	v_max_f32_e32 v15, v13, v8
	v_exp_f32_e32 v8, v9
	v_sub_f32_e32 v9, v13, v15
	v_sub_f32_e32 v13, v14, v15
	v_mul_f32_e32 v9, 0x3fb8aa3b, v9
	v_mul_f32_e32 v12, 0x3fb8aa3b, v12
	v_mul_f32_e32 v13, 0x3fb8aa3b, v13
	v_exp_f32_e32 v9, v9
	v_exp_f32_e32 v12, v12
	v_exp_f32_e32 v13, v13
	ds_write_b128 v5, v[0:3] offset:4144
	v_mov_b32_e32 v0, v15
	ds_write_b128 v5, v[6:9] offset:48
	ds_write_b128 v5, v[10:13] offset:2096
	global_load_dword v88, v[104:105], off offset:512
	global_load_dword v89, v[104:105], off offset:2560
	global_load_dword v90, v[104:105], off offset:528
	global_load_dword v91, v[104:105], off offset:544
	global_load_dword v92, v[104:105], off offset:560
	global_load_dword v93, v[104:105], off offset:2576
	global_load_dword v94, v[104:105], off offset:2592
	global_load_dword v95, v[104:105], off offset:2608
	s_waitcnt vmcnt(32)
	v_mov_b32_e32 v12, v96
	v_mov_b32_e32 v1, v97
	v_mov_b32_e32 v11, v98
	v_mov_b32_e32 v13, v99
	v_mov_b32_e32 v14, v100
	v_mov_b32_e32 v10, v101
	v_mov_b32_e32 v15, v102
	v_mov_b32_e32 v16, v103
	v_add_f32_e32 v2, v0, v1
	v_max_f32_e32 v1, v12, v12
	v_max_f32_e32 v1, v2, v1
	v_max_f32_e32 v3, v11, v11
	v_sub_f32_e32 v2, v2, v1
	v_sub_f32_e32 v6, v12, v1
	v_add_f32_e32 v9, v1, v10
	v_mul_f32_e32 v10, 0x3fb8aa3b, v2
	v_mul_f32_e32 v12, 0x3fb8aa3b, v6
	v_max_f32_e32 v2, v9, v3
	v_max_f32_e32 v7, v13, v13
	v_exp_f32_e32 v6, v10
	v_exp_f32_e32 v10, v12
	v_sub_f32_e32 v3, v9, v2
	v_sub_f32_e32 v9, v11, v2
	v_add_f32_e32 v12, v2, v15
	v_mul_f32_e32 v11, 0x3fb8aa3b, v3
	v_mul_f32_e32 v9, 0x3fb8aa3b, v9
	v_max_f32_e32 v3, v12, v7
	v_max_f32_e32 v8, v14, v14
	v_exp_f32_e32 v7, v11
	v_exp_f32_e32 v11, v9
	v_sub_f32_e32 v9, v12, v3
	v_sub_f32_e32 v12, v13, v3
	v_add_f32_e32 v13, v3, v16
	v_mul_f32_e32 v9, 0x3fb8aa3b, v9
	v_max_f32_e32 v15, v13, v8
	v_exp_f32_e32 v8, v9
	v_sub_f32_e32 v9, v13, v15
	v_sub_f32_e32 v13, v14, v15
	v_mul_f32_e32 v9, 0x3fb8aa3b, v9
	v_mul_f32_e32 v12, 0x3fb8aa3b, v12
	v_mul_f32_e32 v13, 0x3fb8aa3b, v13
	v_exp_f32_e32 v9, v9
	v_exp_f32_e32 v12, v12
	v_exp_f32_e32 v13, v13
	ds_write_b128 v5, v[0:3] offset:4160
	v_mov_b32_e32 v0, v15
	ds_write_b128 v5, v[6:9] offset:64
	ds_write_b128 v5, v[10:13] offset:2112
	global_load_dword v96, v[104:105], off offset:576
	global_load_dword v97, v[104:105], off offset:2624
	global_load_dword v98, v[104:105], off offset:592
	global_load_dword v99, v[104:105], off offset:608
	global_load_dword v100, v[104:105], off offset:624
	global_load_dword v101, v[104:105], off offset:2640
	global_load_dword v102, v[104:105], off offset:2656
	global_load_dword v103, v[104:105], off offset:2672
	s_waitcnt vmcnt(32)
	v_mov_b32_e32 v12, v64
	v_mov_b32_e32 v1, v65
	v_mov_b32_e32 v11, v66
	v_mov_b32_e32 v13, v67
	v_mov_b32_e32 v14, v68
	v_mov_b32_e32 v10, v69
	v_mov_b32_e32 v15, v70
	v_mov_b32_e32 v16, v71
	v_add_f32_e32 v2, v0, v1
	v_max_f32_e32 v1, v12, v12
	v_max_f32_e32 v1, v2, v1
	v_max_f32_e32 v3, v11, v11
	v_sub_f32_e32 v2, v2, v1
	v_sub_f32_e32 v6, v12, v1
	v_add_f32_e32 v9, v1, v10
	v_mul_f32_e32 v10, 0x3fb8aa3b, v2
	v_mul_f32_e32 v12, 0x3fb8aa3b, v6
	v_max_f32_e32 v2, v9, v3
	v_max_f32_e32 v7, v13, v13
	v_exp_f32_e32 v6, v10
	v_exp_f32_e32 v10, v12
	v_sub_f32_e32 v3, v9, v2
	v_sub_f32_e32 v9, v11, v2
	v_add_f32_e32 v12, v2, v15
	v_mul_f32_e32 v11, 0x3fb8aa3b, v3
	v_mul_f32_e32 v9, 0x3fb8aa3b, v9
	v_max_f32_e32 v3, v12, v7
	v_max_f32_e32 v8, v14, v14
	v_exp_f32_e32 v7, v11
	v_exp_f32_e32 v11, v9
	v_sub_f32_e32 v9, v12, v3
	v_sub_f32_e32 v12, v13, v3
	v_add_f32_e32 v13, v3, v16
	v_mul_f32_e32 v9, 0x3fb8aa3b, v9
	v_max_f32_e32 v15, v13, v8
	v_exp_f32_e32 v8, v9
	v_sub_f32_e32 v9, v13, v15
	v_sub_f32_e32 v13, v14, v15
	v_mul_f32_e32 v9, 0x3fb8aa3b, v9
	v_mul_f32_e32 v12, 0x3fb8aa3b, v12
	v_mul_f32_e32 v13, 0x3fb8aa3b, v13
	v_exp_f32_e32 v9, v9
	v_exp_f32_e32 v12, v12
	v_exp_f32_e32 v13, v13
	ds_write_b128 v5, v[0:3] offset:4176
	v_mov_b32_e32 v0, v15
	ds_write_b128 v5, v[6:9] offset:80
	ds_write_b128 v5, v[10:13] offset:2128
	global_load_dword v64, v[104:105], off offset:640
	global_load_dword v65, v[104:105], off offset:2688
	global_load_dword v66, v[104:105], off offset:656
	global_load_dword v67, v[104:105], off offset:672
	global_load_dword v68, v[104:105], off offset:688
	global_load_dword v69, v[104:105], off offset:2704
	global_load_dword v70, v[104:105], off offset:2720
	global_load_dword v71, v[104:105], off offset:2736
	s_waitcnt vmcnt(32)
	v_mov_b32_e32 v12, v72
	v_mov_b32_e32 v1, v73
	v_mov_b32_e32 v11, v74
	v_mov_b32_e32 v13, v75
	v_mov_b32_e32 v14, v76
	v_mov_b32_e32 v10, v77
	v_mov_b32_e32 v15, v78
	v_mov_b32_e32 v16, v79
	v_add_f32_e32 v2, v0, v1
	v_max_f32_e32 v1, v12, v12
	v_max_f32_e32 v1, v2, v1
	v_max_f32_e32 v3, v11, v11
	v_sub_f32_e32 v2, v2, v1
	v_sub_f32_e32 v6, v12, v1
	v_add_f32_e32 v9, v1, v10
	v_mul_f32_e32 v10, 0x3fb8aa3b, v2
	v_mul_f32_e32 v12, 0x3fb8aa3b, v6
	v_max_f32_e32 v2, v9, v3
	v_max_f32_e32 v7, v13, v13
	v_exp_f32_e32 v6, v10
	v_exp_f32_e32 v10, v12
	v_sub_f32_e32 v3, v9, v2
	v_sub_f32_e32 v9, v11, v2
	v_add_f32_e32 v12, v2, v15
	v_mul_f32_e32 v11, 0x3fb8aa3b, v3
	v_mul_f32_e32 v9, 0x3fb8aa3b, v9
	v_max_f32_e32 v3, v12, v7
	v_max_f32_e32 v8, v14, v14
	v_exp_f32_e32 v7, v11
	v_exp_f32_e32 v11, v9
	v_sub_f32_e32 v9, v12, v3
	v_sub_f32_e32 v12, v13, v3
	v_add_f32_e32 v13, v3, v16
	v_mul_f32_e32 v9, 0x3fb8aa3b, v9
	v_max_f32_e32 v15, v13, v8
	v_exp_f32_e32 v8, v9
	v_sub_f32_e32 v9, v13, v15
	v_sub_f32_e32 v13, v14, v15
	v_mul_f32_e32 v9, 0x3fb8aa3b, v9
	v_mul_f32_e32 v12, 0x3fb8aa3b, v12
	v_mul_f32_e32 v13, 0x3fb8aa3b, v13
	v_exp_f32_e32 v9, v9
	v_exp_f32_e32 v12, v12
	v_exp_f32_e32 v13, v13
	ds_write_b128 v5, v[0:3] offset:4192
	v_mov_b32_e32 v0, v15
	ds_write_b128 v5, v[6:9] offset:96
	ds_write_b128 v5, v[10:13] offset:2144
	global_load_dword v72, v[104:105], off offset:704
	global_load_dword v73, v[104:105], off offset:2752
	global_load_dword v74, v[104:105], off offset:720
	global_load_dword v75, v[104:105], off offset:736
	global_load_dword v76, v[104:105], off offset:752
	global_load_dword v77, v[104:105], off offset:2768
	global_load_dword v78, v[104:105], off offset:2784
	global_load_dword v79, v[104:105], off offset:2800
	s_waitcnt vmcnt(32)
	v_mov_b32_e32 v12, v80
	v_mov_b32_e32 v1, v81
	v_mov_b32_e32 v11, v82
	v_mov_b32_e32 v13, v83
	v_mov_b32_e32 v14, v84
	v_mov_b32_e32 v10, v85
	v_mov_b32_e32 v15, v86
	v_mov_b32_e32 v16, v87
	v_add_f32_e32 v2, v0, v1
	v_max_f32_e32 v1, v12, v12
	v_max_f32_e32 v1, v2, v1
	v_max_f32_e32 v3, v11, v11
	v_sub_f32_e32 v2, v2, v1
	v_sub_f32_e32 v6, v12, v1
	v_add_f32_e32 v9, v1, v10
	v_mul_f32_e32 v10, 0x3fb8aa3b, v2
	v_mul_f32_e32 v12, 0x3fb8aa3b, v6
	v_max_f32_e32 v2, v9, v3
	v_max_f32_e32 v7, v13, v13
	v_exp_f32_e32 v6, v10
	v_exp_f32_e32 v10, v12
	v_sub_f32_e32 v3, v9, v2
	v_sub_f32_e32 v9, v11, v2
	v_add_f32_e32 v12, v2, v15
	v_mul_f32_e32 v11, 0x3fb8aa3b, v3
	v_mul_f32_e32 v9, 0x3fb8aa3b, v9
	v_max_f32_e32 v3, v12, v7
	v_max_f32_e32 v8, v14, v14
	v_exp_f32_e32 v7, v11
	v_exp_f32_e32 v11, v9
	v_sub_f32_e32 v9, v12, v3
	v_sub_f32_e32 v12, v13, v3
	v_add_f32_e32 v13, v3, v16
	v_mul_f32_e32 v9, 0x3fb8aa3b, v9
	v_max_f32_e32 v15, v13, v8
	v_exp_f32_e32 v8, v9
	v_sub_f32_e32 v9, v13, v15
	v_sub_f32_e32 v13, v14, v15
	v_mul_f32_e32 v9, 0x3fb8aa3b, v9
	v_mul_f32_e32 v12, 0x3fb8aa3b, v12
	v_mul_f32_e32 v13, 0x3fb8aa3b, v13
	v_exp_f32_e32 v9, v9
	v_exp_f32_e32 v12, v12
	v_exp_f32_e32 v13, v13
	ds_write_b128 v5, v[0:3] offset:4208
	v_mov_b32_e32 v0, v15
	ds_write_b128 v5, v[6:9] offset:112
	ds_write_b128 v5, v[10:13] offset:2160
	global_load_dword v80, v[104:105], off offset:768
	global_load_dword v81, v[104:105], off offset:2816
	global_load_dword v82, v[104:105], off offset:784
	global_load_dword v83, v[104:105], off offset:800
	global_load_dword v84, v[104:105], off offset:816
	global_load_dword v85, v[104:105], off offset:2832
	global_load_dword v86, v[104:105], off offset:2848
	global_load_dword v87, v[104:105], off offset:2864
	s_waitcnt vmcnt(32)
	v_mov_b32_e32 v12, v88
	v_mov_b32_e32 v1, v89
	v_mov_b32_e32 v11, v90
	v_mov_b32_e32 v13, v91
	v_mov_b32_e32 v14, v92
	v_mov_b32_e32 v10, v93
	v_mov_b32_e32 v15, v94
	v_mov_b32_e32 v16, v95
	v_add_f32_e32 v2, v0, v1
	v_max_f32_e32 v1, v12, v12
	v_max_f32_e32 v1, v2, v1
	v_max_f32_e32 v3, v11, v11
	v_sub_f32_e32 v2, v2, v1
	v_sub_f32_e32 v6, v12, v1
	v_add_f32_e32 v9, v1, v10
	v_mul_f32_e32 v10, 0x3fb8aa3b, v2
	v_mul_f32_e32 v12, 0x3fb8aa3b, v6
	v_max_f32_e32 v2, v9, v3
	v_max_f32_e32 v7, v13, v13
	v_exp_f32_e32 v6, v10
	v_exp_f32_e32 v10, v12
	v_sub_f32_e32 v3, v9, v2
	v_sub_f32_e32 v9, v11, v2
	v_add_f32_e32 v12, v2, v15
	v_mul_f32_e32 v11, 0x3fb8aa3b, v3
	v_mul_f32_e32 v9, 0x3fb8aa3b, v9
	v_max_f32_e32 v3, v12, v7
	v_max_f32_e32 v8, v14, v14
	v_exp_f32_e32 v7, v11
	v_exp_f32_e32 v11, v9
	v_sub_f32_e32 v9, v12, v3
	v_sub_f32_e32 v12, v13, v3
	v_add_f32_e32 v13, v3, v16
	v_mul_f32_e32 v9, 0x3fb8aa3b, v9
	v_max_f32_e32 v15, v13, v8
	v_exp_f32_e32 v8, v9
	v_sub_f32_e32 v9, v13, v15
	v_sub_f32_e32 v13, v14, v15
	v_mul_f32_e32 v9, 0x3fb8aa3b, v9
	v_mul_f32_e32 v12, 0x3fb8aa3b, v12
	v_mul_f32_e32 v13, 0x3fb8aa3b, v13
	v_exp_f32_e32 v9, v9
	v_exp_f32_e32 v12, v12
	v_exp_f32_e32 v13, v13
	ds_write_b128 v5, v[0:3] offset:4224
	v_mov_b32_e32 v0, v15
	ds_write_b128 v5, v[6:9] offset:128
	ds_write_b128 v5, v[10:13] offset:2176
	global_load_dword v88, v[104:105], off offset:832
	global_load_dword v89, v[104:105], off offset:2880
	global_load_dword v90, v[104:105], off offset:848
	global_load_dword v91, v[104:105], off offset:864
	global_load_dword v92, v[104:105], off offset:880
	global_load_dword v93, v[104:105], off offset:2896
	global_load_dword v94, v[104:105], off offset:2912
	global_load_dword v95, v[104:105], off offset:2928
	s_waitcnt vmcnt(32)
	v_mov_b32_e32 v12, v96
	v_mov_b32_e32 v1, v97
	v_mov_b32_e32 v11, v98
	v_mov_b32_e32 v13, v99
	v_mov_b32_e32 v14, v100
	v_mov_b32_e32 v10, v101
	v_mov_b32_e32 v15, v102
	v_mov_b32_e32 v16, v103
	v_add_f32_e32 v2, v0, v1
	v_max_f32_e32 v1, v12, v12
	v_max_f32_e32 v1, v2, v1
	v_max_f32_e32 v3, v11, v11
	v_sub_f32_e32 v2, v2, v1
	v_sub_f32_e32 v6, v12, v1
	v_add_f32_e32 v9, v1, v10
	v_mul_f32_e32 v10, 0x3fb8aa3b, v2
	v_mul_f32_e32 v12, 0x3fb8aa3b, v6
	v_max_f32_e32 v2, v9, v3
	v_max_f32_e32 v7, v13, v13
	v_exp_f32_e32 v6, v10
	v_exp_f32_e32 v10, v12
	v_sub_f32_e32 v3, v9, v2
	v_sub_f32_e32 v9, v11, v2
	v_add_f32_e32 v12, v2, v15
	v_mul_f32_e32 v11, 0x3fb8aa3b, v3
	v_mul_f32_e32 v9, 0x3fb8aa3b, v9
	v_max_f32_e32 v3, v12, v7
	v_max_f32_e32 v8, v14, v14
	v_exp_f32_e32 v7, v11
	v_exp_f32_e32 v11, v9
	v_sub_f32_e32 v9, v12, v3
	v_sub_f32_e32 v12, v13, v3
	v_add_f32_e32 v13, v3, v16
	v_mul_f32_e32 v9, 0x3fb8aa3b, v9
	v_max_f32_e32 v15, v13, v8
	v_exp_f32_e32 v8, v9
	v_sub_f32_e32 v9, v13, v15
	v_sub_f32_e32 v13, v14, v15
	v_mul_f32_e32 v9, 0x3fb8aa3b, v9
	v_mul_f32_e32 v12, 0x3fb8aa3b, v12
	v_mul_f32_e32 v13, 0x3fb8aa3b, v13
	v_exp_f32_e32 v9, v9
	v_exp_f32_e32 v12, v12
	v_exp_f32_e32 v13, v13
	ds_write_b128 v5, v[0:3] offset:4240
	v_mov_b32_e32 v0, v15
	ds_write_b128 v5, v[6:9] offset:144
	ds_write_b128 v5, v[10:13] offset:2192
	global_load_dword v96, v[104:105], off offset:896
	global_load_dword v97, v[104:105], off offset:2944
	global_load_dword v98, v[104:105], off offset:912
	global_load_dword v99, v[104:105], off offset:928
	global_load_dword v100, v[104:105], off offset:944
	global_load_dword v101, v[104:105], off offset:2960
	global_load_dword v102, v[104:105], off offset:2976
	global_load_dword v103, v[104:105], off offset:2992
	s_waitcnt vmcnt(32)
	v_mov_b32_e32 v12, v64
	v_mov_b32_e32 v1, v65
	v_mov_b32_e32 v11, v66
	v_mov_b32_e32 v13, v67
	v_mov_b32_e32 v14, v68
	v_mov_b32_e32 v10, v69
	v_mov_b32_e32 v15, v70
	v_mov_b32_e32 v16, v71
	v_add_f32_e32 v2, v0, v1
	v_max_f32_e32 v1, v12, v12
	v_max_f32_e32 v1, v2, v1
	v_max_f32_e32 v3, v11, v11
	v_sub_f32_e32 v2, v2, v1
	v_sub_f32_e32 v6, v12, v1
	v_add_f32_e32 v9, v1, v10
	v_mul_f32_e32 v10, 0x3fb8aa3b, v2
	v_mul_f32_e32 v12, 0x3fb8aa3b, v6
	v_max_f32_e32 v2, v9, v3
	v_max_f32_e32 v7, v13, v13
	v_exp_f32_e32 v6, v10
	v_exp_f32_e32 v10, v12
	v_sub_f32_e32 v3, v9, v2
	v_sub_f32_e32 v9, v11, v2
	v_add_f32_e32 v12, v2, v15
	v_mul_f32_e32 v11, 0x3fb8aa3b, v3
	v_mul_f32_e32 v9, 0x3fb8aa3b, v9
	v_max_f32_e32 v3, v12, v7
	v_max_f32_e32 v8, v14, v14
	v_exp_f32_e32 v7, v11
	v_exp_f32_e32 v11, v9
	v_sub_f32_e32 v9, v12, v3
	v_sub_f32_e32 v12, v13, v3
	v_add_f32_e32 v13, v3, v16
	v_mul_f32_e32 v9, 0x3fb8aa3b, v9
	v_max_f32_e32 v15, v13, v8
	v_exp_f32_e32 v8, v9
	v_sub_f32_e32 v9, v13, v15
	v_sub_f32_e32 v13, v14, v15
	v_mul_f32_e32 v9, 0x3fb8aa3b, v9
	v_mul_f32_e32 v12, 0x3fb8aa3b, v12
	v_mul_f32_e32 v13, 0x3fb8aa3b, v13
	v_exp_f32_e32 v9, v9
	v_exp_f32_e32 v12, v12
	v_exp_f32_e32 v13, v13
	ds_write_b128 v5, v[0:3] offset:4256
	v_mov_b32_e32 v0, v15
	ds_write_b128 v5, v[6:9] offset:160
	ds_write_b128 v5, v[10:13] offset:2208
	global_load_dword v64, v[104:105], off offset:960
	global_load_dword v65, v[104:105], off offset:3008
	global_load_dword v66, v[104:105], off offset:976
	global_load_dword v67, v[104:105], off offset:992
	global_load_dword v68, v[104:105], off offset:1008
	global_load_dword v69, v[104:105], off offset:3024
	global_load_dword v70, v[104:105], off offset:3040
	global_load_dword v71, v[104:105], off offset:3056
	s_waitcnt vmcnt(32)
	v_mov_b32_e32 v12, v72
	v_mov_b32_e32 v1, v73
	v_mov_b32_e32 v11, v74
	v_mov_b32_e32 v13, v75
	v_mov_b32_e32 v14, v76
	v_mov_b32_e32 v10, v77
	v_mov_b32_e32 v15, v78
	v_mov_b32_e32 v16, v79
	v_add_f32_e32 v2, v0, v1
	v_max_f32_e32 v1, v12, v12
	v_max_f32_e32 v1, v2, v1
	v_max_f32_e32 v3, v11, v11
	v_sub_f32_e32 v2, v2, v1
	v_sub_f32_e32 v6, v12, v1
	v_add_f32_e32 v9, v1, v10
	v_mul_f32_e32 v10, 0x3fb8aa3b, v2
	v_mul_f32_e32 v12, 0x3fb8aa3b, v6
	v_max_f32_e32 v2, v9, v3
	v_max_f32_e32 v7, v13, v13
	v_exp_f32_e32 v6, v10
	v_exp_f32_e32 v10, v12
	v_sub_f32_e32 v3, v9, v2
	v_sub_f32_e32 v9, v11, v2
	v_add_f32_e32 v12, v2, v15
	v_mul_f32_e32 v11, 0x3fb8aa3b, v3
	v_mul_f32_e32 v9, 0x3fb8aa3b, v9
	v_max_f32_e32 v3, v12, v7
	v_max_f32_e32 v8, v14, v14
	v_exp_f32_e32 v7, v11
	v_exp_f32_e32 v11, v9
	v_sub_f32_e32 v9, v12, v3
	v_sub_f32_e32 v12, v13, v3
	v_add_f32_e32 v13, v3, v16
	v_mul_f32_e32 v9, 0x3fb8aa3b, v9
	v_max_f32_e32 v15, v13, v8
	v_exp_f32_e32 v8, v9
	v_sub_f32_e32 v9, v13, v15
	v_sub_f32_e32 v13, v14, v15
	v_mul_f32_e32 v9, 0x3fb8aa3b, v9
	v_mul_f32_e32 v12, 0x3fb8aa3b, v12
	v_mul_f32_e32 v13, 0x3fb8aa3b, v13
	v_exp_f32_e32 v9, v9
	v_exp_f32_e32 v12, v12
	v_exp_f32_e32 v13, v13
	ds_write_b128 v5, v[0:3] offset:4272
	v_mov_b32_e32 v0, v15
	ds_write_b128 v5, v[6:9] offset:176
	ds_write_b128 v5, v[10:13] offset:2224
	global_load_dword v72, v[104:105], off offset:1024
	global_load_dword v73, v[104:105], off offset:3072
	global_load_dword v74, v[104:105], off offset:1040
	global_load_dword v75, v[104:105], off offset:1056
	global_load_dword v76, v[104:105], off offset:1072
	global_load_dword v77, v[104:105], off offset:3088
	global_load_dword v78, v[104:105], off offset:3104
	global_load_dword v79, v[104:105], off offset:3120
	s_waitcnt vmcnt(32)
	v_mov_b32_e32 v12, v80
	v_mov_b32_e32 v1, v81
	v_mov_b32_e32 v11, v82
	v_mov_b32_e32 v13, v83
	v_mov_b32_e32 v14, v84
	v_mov_b32_e32 v10, v85
	v_mov_b32_e32 v15, v86
	v_mov_b32_e32 v16, v87
	v_add_f32_e32 v2, v0, v1
	v_max_f32_e32 v1, v12, v12
	v_max_f32_e32 v1, v2, v1
	v_max_f32_e32 v3, v11, v11
	v_sub_f32_e32 v2, v2, v1
	v_sub_f32_e32 v6, v12, v1
	v_add_f32_e32 v9, v1, v10
	v_mul_f32_e32 v10, 0x3fb8aa3b, v2
	v_mul_f32_e32 v12, 0x3fb8aa3b, v6
	v_max_f32_e32 v2, v9, v3
	v_max_f32_e32 v7, v13, v13
	v_exp_f32_e32 v6, v10
	v_exp_f32_e32 v10, v12
	v_sub_f32_e32 v3, v9, v2
	v_sub_f32_e32 v9, v11, v2
	v_add_f32_e32 v12, v2, v15
	v_mul_f32_e32 v11, 0x3fb8aa3b, v3
	v_mul_f32_e32 v9, 0x3fb8aa3b, v9
	v_max_f32_e32 v3, v12, v7
	v_max_f32_e32 v8, v14, v14
	v_exp_f32_e32 v7, v11
	v_exp_f32_e32 v11, v9
	v_sub_f32_e32 v9, v12, v3
	v_sub_f32_e32 v12, v13, v3
	v_add_f32_e32 v13, v3, v16
	v_mul_f32_e32 v9, 0x3fb8aa3b, v9
	v_max_f32_e32 v15, v13, v8
	v_exp_f32_e32 v8, v9
	v_sub_f32_e32 v9, v13, v15
	v_sub_f32_e32 v13, v14, v15
	v_mul_f32_e32 v9, 0x3fb8aa3b, v9
	v_mul_f32_e32 v12, 0x3fb8aa3b, v12
	v_mul_f32_e32 v13, 0x3fb8aa3b, v13
	v_exp_f32_e32 v9, v9
	v_exp_f32_e32 v12, v12
	v_exp_f32_e32 v13, v13
	ds_write_b128 v5, v[0:3] offset:4288
	v_mov_b32_e32 v0, v15
	ds_write_b128 v5, v[6:9] offset:192
	ds_write_b128 v5, v[10:13] offset:2240
	global_load_dword v80, v[104:105], off offset:1088
	global_load_dword v81, v[104:105], off offset:3136
	global_load_dword v82, v[104:105], off offset:1104
	global_load_dword v83, v[104:105], off offset:1120
	global_load_dword v84, v[104:105], off offset:1136
	global_load_dword v85, v[104:105], off offset:3152
	global_load_dword v86, v[104:105], off offset:3168
	global_load_dword v87, v[104:105], off offset:3184
	s_waitcnt vmcnt(32)
	v_mov_b32_e32 v12, v88
	v_mov_b32_e32 v1, v89
	v_mov_b32_e32 v11, v90
	v_mov_b32_e32 v13, v91
	v_mov_b32_e32 v14, v92
	v_mov_b32_e32 v10, v93
	v_mov_b32_e32 v15, v94
	v_mov_b32_e32 v16, v95
	v_add_f32_e32 v2, v0, v1
	v_max_f32_e32 v1, v12, v12
	v_max_f32_e32 v1, v2, v1
	v_max_f32_e32 v3, v11, v11
	v_sub_f32_e32 v2, v2, v1
	v_sub_f32_e32 v6, v12, v1
	v_add_f32_e32 v9, v1, v10
	v_mul_f32_e32 v10, 0x3fb8aa3b, v2
	v_mul_f32_e32 v12, 0x3fb8aa3b, v6
	v_max_f32_e32 v2, v9, v3
	v_max_f32_e32 v7, v13, v13
	v_exp_f32_e32 v6, v10
	v_exp_f32_e32 v10, v12
	v_sub_f32_e32 v3, v9, v2
	v_sub_f32_e32 v9, v11, v2
	v_add_f32_e32 v12, v2, v15
	v_mul_f32_e32 v11, 0x3fb8aa3b, v3
	v_mul_f32_e32 v9, 0x3fb8aa3b, v9
	v_max_f32_e32 v3, v12, v7
	v_max_f32_e32 v8, v14, v14
	v_exp_f32_e32 v7, v11
	v_exp_f32_e32 v11, v9
	v_sub_f32_e32 v9, v12, v3
	v_sub_f32_e32 v12, v13, v3
	v_add_f32_e32 v13, v3, v16
	v_mul_f32_e32 v9, 0x3fb8aa3b, v9
	v_max_f32_e32 v15, v13, v8
	v_exp_f32_e32 v8, v9
	v_sub_f32_e32 v9, v13, v15
	v_sub_f32_e32 v13, v14, v15
	v_mul_f32_e32 v9, 0x3fb8aa3b, v9
	v_mul_f32_e32 v12, 0x3fb8aa3b, v12
	v_mul_f32_e32 v13, 0x3fb8aa3b, v13
	v_exp_f32_e32 v9, v9
	v_exp_f32_e32 v12, v12
	v_exp_f32_e32 v13, v13
	ds_write_b128 v5, v[0:3] offset:4304
	v_mov_b32_e32 v0, v15
	ds_write_b128 v5, v[6:9] offset:208
	ds_write_b128 v5, v[10:13] offset:2256
	global_load_dword v88, v[104:105], off offset:1152
	global_load_dword v89, v[104:105], off offset:3200
	global_load_dword v90, v[104:105], off offset:1168
	global_load_dword v91, v[104:105], off offset:1184
	global_load_dword v92, v[104:105], off offset:1200
	global_load_dword v93, v[104:105], off offset:3216
	global_load_dword v94, v[104:105], off offset:3232
	global_load_dword v95, v[104:105], off offset:3248
	s_waitcnt vmcnt(32)
	v_mov_b32_e32 v12, v96
	v_mov_b32_e32 v1, v97
	v_mov_b32_e32 v11, v98
	v_mov_b32_e32 v13, v99
	v_mov_b32_e32 v14, v100
	v_mov_b32_e32 v10, v101
	v_mov_b32_e32 v15, v102
	v_mov_b32_e32 v16, v103
	v_add_f32_e32 v2, v0, v1
	v_max_f32_e32 v1, v12, v12
	v_max_f32_e32 v1, v2, v1
	v_max_f32_e32 v3, v11, v11
	v_sub_f32_e32 v2, v2, v1
	v_sub_f32_e32 v6, v12, v1
	v_add_f32_e32 v9, v1, v10
	v_mul_f32_e32 v10, 0x3fb8aa3b, v2
	v_mul_f32_e32 v12, 0x3fb8aa3b, v6
	v_max_f32_e32 v2, v9, v3
	v_max_f32_e32 v7, v13, v13
	v_exp_f32_e32 v6, v10
	v_exp_f32_e32 v10, v12
	v_sub_f32_e32 v3, v9, v2
	v_sub_f32_e32 v9, v11, v2
	v_add_f32_e32 v12, v2, v15
	v_mul_f32_e32 v11, 0x3fb8aa3b, v3
	v_mul_f32_e32 v9, 0x3fb8aa3b, v9
	v_max_f32_e32 v3, v12, v7
	v_max_f32_e32 v8, v14, v14
	v_exp_f32_e32 v7, v11
	v_exp_f32_e32 v11, v9
	v_sub_f32_e32 v9, v12, v3
	v_sub_f32_e32 v12, v13, v3
	v_add_f32_e32 v13, v3, v16
	v_mul_f32_e32 v9, 0x3fb8aa3b, v9
	v_max_f32_e32 v15, v13, v8
	v_exp_f32_e32 v8, v9
	v_sub_f32_e32 v9, v13, v15
	v_sub_f32_e32 v13, v14, v15
	v_mul_f32_e32 v9, 0x3fb8aa3b, v9
	v_mul_f32_e32 v12, 0x3fb8aa3b, v12
	v_mul_f32_e32 v13, 0x3fb8aa3b, v13
	v_exp_f32_e32 v9, v9
	v_exp_f32_e32 v12, v12
	v_exp_f32_e32 v13, v13
	ds_write_b128 v5, v[0:3] offset:4320
	v_mov_b32_e32 v0, v15
	ds_write_b128 v5, v[6:9] offset:224
	ds_write_b128 v5, v[10:13] offset:2272
	global_load_dword v96, v[104:105], off offset:1216
	global_load_dword v97, v[104:105], off offset:3264
	global_load_dword v98, v[104:105], off offset:1232
	global_load_dword v99, v[104:105], off offset:1248
	global_load_dword v100, v[104:105], off offset:1264
	global_load_dword v101, v[104:105], off offset:3280
	global_load_dword v102, v[104:105], off offset:3296
	global_load_dword v103, v[104:105], off offset:3312
	s_waitcnt vmcnt(32)
	v_mov_b32_e32 v12, v64
	v_mov_b32_e32 v1, v65
	v_mov_b32_e32 v11, v66
	v_mov_b32_e32 v13, v67
	v_mov_b32_e32 v14, v68
	v_mov_b32_e32 v10, v69
	v_mov_b32_e32 v15, v70
	v_mov_b32_e32 v16, v71
	v_add_f32_e32 v2, v0, v1
	v_max_f32_e32 v1, v12, v12
	v_max_f32_e32 v1, v2, v1
	v_max_f32_e32 v3, v11, v11
	v_sub_f32_e32 v2, v2, v1
	v_sub_f32_e32 v6, v12, v1
	v_add_f32_e32 v9, v1, v10
	v_mul_f32_e32 v10, 0x3fb8aa3b, v2
	v_mul_f32_e32 v12, 0x3fb8aa3b, v6
	v_max_f32_e32 v2, v9, v3
	v_max_f32_e32 v7, v13, v13
	v_exp_f32_e32 v6, v10
	v_exp_f32_e32 v10, v12
	v_sub_f32_e32 v3, v9, v2
	v_sub_f32_e32 v9, v11, v2
	v_add_f32_e32 v12, v2, v15
	v_mul_f32_e32 v11, 0x3fb8aa3b, v3
	v_mul_f32_e32 v9, 0x3fb8aa3b, v9
	v_max_f32_e32 v3, v12, v7
	v_max_f32_e32 v8, v14, v14
	v_exp_f32_e32 v7, v11
	v_exp_f32_e32 v11, v9
	v_sub_f32_e32 v9, v12, v3
	v_sub_f32_e32 v12, v13, v3
	v_add_f32_e32 v13, v3, v16
	v_mul_f32_e32 v9, 0x3fb8aa3b, v9
	v_max_f32_e32 v15, v13, v8
	v_exp_f32_e32 v8, v9
	v_sub_f32_e32 v9, v13, v15
	v_sub_f32_e32 v13, v14, v15
	v_mul_f32_e32 v9, 0x3fb8aa3b, v9
	v_mul_f32_e32 v12, 0x3fb8aa3b, v12
	v_mul_f32_e32 v13, 0x3fb8aa3b, v13
	v_exp_f32_e32 v9, v9
	v_exp_f32_e32 v12, v12
	v_exp_f32_e32 v13, v13
	ds_write_b128 v5, v[0:3] offset:4336
	v_mov_b32_e32 v0, v15
	ds_write_b128 v5, v[6:9] offset:240
	ds_write_b128 v5, v[10:13] offset:2288
	global_load_dword v64, v[104:105], off offset:1280
	global_load_dword v65, v[104:105], off offset:3328
	global_load_dword v66, v[104:105], off offset:1296
	global_load_dword v67, v[104:105], off offset:1312
	global_load_dword v68, v[104:105], off offset:1328
	global_load_dword v69, v[104:105], off offset:3344
	global_load_dword v70, v[104:105], off offset:3360
	global_load_dword v71, v[104:105], off offset:3376
	s_waitcnt vmcnt(32)
	v_mov_b32_e32 v12, v72
	v_mov_b32_e32 v1, v73
	v_mov_b32_e32 v11, v74
	v_mov_b32_e32 v13, v75
	v_mov_b32_e32 v14, v76
	v_mov_b32_e32 v10, v77
	v_mov_b32_e32 v15, v78
	v_mov_b32_e32 v16, v79
	v_add_f32_e32 v2, v0, v1
	v_max_f32_e32 v1, v12, v12
	v_max_f32_e32 v1, v2, v1
	v_max_f32_e32 v3, v11, v11
	v_sub_f32_e32 v2, v2, v1
	v_sub_f32_e32 v6, v12, v1
	v_add_f32_e32 v9, v1, v10
	v_mul_f32_e32 v10, 0x3fb8aa3b, v2
	v_mul_f32_e32 v12, 0x3fb8aa3b, v6
	v_max_f32_e32 v2, v9, v3
	v_max_f32_e32 v7, v13, v13
	v_exp_f32_e32 v6, v10
	v_exp_f32_e32 v10, v12
	v_sub_f32_e32 v3, v9, v2
	v_sub_f32_e32 v9, v11, v2
	v_add_f32_e32 v12, v2, v15
	v_mul_f32_e32 v11, 0x3fb8aa3b, v3
	v_mul_f32_e32 v9, 0x3fb8aa3b, v9
	v_max_f32_e32 v3, v12, v7
	v_max_f32_e32 v8, v14, v14
	v_exp_f32_e32 v7, v11
	v_exp_f32_e32 v11, v9
	v_sub_f32_e32 v9, v12, v3
	v_sub_f32_e32 v12, v13, v3
	v_add_f32_e32 v13, v3, v16
	v_mul_f32_e32 v9, 0x3fb8aa3b, v9
	v_max_f32_e32 v15, v13, v8
	v_exp_f32_e32 v8, v9
	v_sub_f32_e32 v9, v13, v15
	v_sub_f32_e32 v13, v14, v15
	v_mul_f32_e32 v9, 0x3fb8aa3b, v9
	v_mul_f32_e32 v12, 0x3fb8aa3b, v12
	v_mul_f32_e32 v13, 0x3fb8aa3b, v13
	v_exp_f32_e32 v9, v9
	v_exp_f32_e32 v12, v12
	v_exp_f32_e32 v13, v13
	ds_write_b128 v5, v[0:3] offset:4352
	v_mov_b32_e32 v0, v15
	ds_write_b128 v5, v[6:9] offset:256
	ds_write_b128 v5, v[10:13] offset:2304
	global_load_dword v72, v[104:105], off offset:1344
	global_load_dword v73, v[104:105], off offset:3392
	global_load_dword v74, v[104:105], off offset:1360
	global_load_dword v75, v[104:105], off offset:1376
	global_load_dword v76, v[104:105], off offset:1392
	global_load_dword v77, v[104:105], off offset:3408
	global_load_dword v78, v[104:105], off offset:3424
	global_load_dword v79, v[104:105], off offset:3440
	s_waitcnt vmcnt(32)
	v_mov_b32_e32 v12, v80
	v_mov_b32_e32 v1, v81
	v_mov_b32_e32 v11, v82
	v_mov_b32_e32 v13, v83
	v_mov_b32_e32 v14, v84
	v_mov_b32_e32 v10, v85
	v_mov_b32_e32 v15, v86
	v_mov_b32_e32 v16, v87
	v_add_f32_e32 v2, v0, v1
	v_max_f32_e32 v1, v12, v12
	v_max_f32_e32 v1, v2, v1
	v_max_f32_e32 v3, v11, v11
	v_sub_f32_e32 v2, v2, v1
	v_sub_f32_e32 v6, v12, v1
	v_add_f32_e32 v9, v1, v10
	v_mul_f32_e32 v10, 0x3fb8aa3b, v2
	v_mul_f32_e32 v12, 0x3fb8aa3b, v6
	v_max_f32_e32 v2, v9, v3
	v_max_f32_e32 v7, v13, v13
	v_exp_f32_e32 v6, v10
	v_exp_f32_e32 v10, v12
	v_sub_f32_e32 v3, v9, v2
	v_sub_f32_e32 v9, v11, v2
	v_add_f32_e32 v12, v2, v15
	v_mul_f32_e32 v11, 0x3fb8aa3b, v3
	v_mul_f32_e32 v9, 0x3fb8aa3b, v9
	v_max_f32_e32 v3, v12, v7
	v_max_f32_e32 v8, v14, v14
	v_exp_f32_e32 v7, v11
	v_exp_f32_e32 v11, v9
	v_sub_f32_e32 v9, v12, v3
	v_sub_f32_e32 v12, v13, v3
	v_add_f32_e32 v13, v3, v16
	v_mul_f32_e32 v9, 0x3fb8aa3b, v9
	v_max_f32_e32 v15, v13, v8
	v_exp_f32_e32 v8, v9
	v_sub_f32_e32 v9, v13, v15
	v_sub_f32_e32 v13, v14, v15
	v_mul_f32_e32 v9, 0x3fb8aa3b, v9
	v_mul_f32_e32 v12, 0x3fb8aa3b, v12
	v_mul_f32_e32 v13, 0x3fb8aa3b, v13
	v_exp_f32_e32 v9, v9
	v_exp_f32_e32 v12, v12
	v_exp_f32_e32 v13, v13
	ds_write_b128 v5, v[0:3] offset:4368
	v_mov_b32_e32 v0, v15
	ds_write_b128 v5, v[6:9] offset:272
	ds_write_b128 v5, v[10:13] offset:2320
	global_load_dword v80, v[104:105], off offset:1408
	global_load_dword v81, v[104:105], off offset:3456
	global_load_dword v82, v[104:105], off offset:1424
	global_load_dword v83, v[104:105], off offset:1440
	global_load_dword v84, v[104:105], off offset:1456
	global_load_dword v85, v[104:105], off offset:3472
	global_load_dword v86, v[104:105], off offset:3488
	global_load_dword v87, v[104:105], off offset:3504
	s_waitcnt vmcnt(32)
	v_mov_b32_e32 v12, v88
	v_mov_b32_e32 v1, v89
	v_mov_b32_e32 v11, v90
	v_mov_b32_e32 v13, v91
	v_mov_b32_e32 v14, v92
	v_mov_b32_e32 v10, v93
	v_mov_b32_e32 v15, v94
	v_mov_b32_e32 v16, v95
	v_add_f32_e32 v2, v0, v1
	v_max_f32_e32 v1, v12, v12
	v_max_f32_e32 v1, v2, v1
	v_max_f32_e32 v3, v11, v11
	v_sub_f32_e32 v2, v2, v1
	v_sub_f32_e32 v6, v12, v1
	v_add_f32_e32 v9, v1, v10
	v_mul_f32_e32 v10, 0x3fb8aa3b, v2
	v_mul_f32_e32 v12, 0x3fb8aa3b, v6
	v_max_f32_e32 v2, v9, v3
	v_max_f32_e32 v7, v13, v13
	v_exp_f32_e32 v6, v10
	v_exp_f32_e32 v10, v12
	v_sub_f32_e32 v3, v9, v2
	v_sub_f32_e32 v9, v11, v2
	v_add_f32_e32 v12, v2, v15
	v_mul_f32_e32 v11, 0x3fb8aa3b, v3
	v_mul_f32_e32 v9, 0x3fb8aa3b, v9
	v_max_f32_e32 v3, v12, v7
	v_max_f32_e32 v8, v14, v14
	v_exp_f32_e32 v7, v11
	v_exp_f32_e32 v11, v9
	v_sub_f32_e32 v9, v12, v3
	v_sub_f32_e32 v12, v13, v3
	v_add_f32_e32 v13, v3, v16
	v_mul_f32_e32 v9, 0x3fb8aa3b, v9
	v_max_f32_e32 v15, v13, v8
	v_exp_f32_e32 v8, v9
	v_sub_f32_e32 v9, v13, v15
	v_sub_f32_e32 v13, v14, v15
	v_mul_f32_e32 v9, 0x3fb8aa3b, v9
	v_mul_f32_e32 v12, 0x3fb8aa3b, v12
	v_mul_f32_e32 v13, 0x3fb8aa3b, v13
	v_exp_f32_e32 v9, v9
	v_exp_f32_e32 v12, v12
	v_exp_f32_e32 v13, v13
	ds_write_b128 v5, v[0:3] offset:4384
	v_mov_b32_e32 v0, v15
	ds_write_b128 v5, v[6:9] offset:288
	ds_write_b128 v5, v[10:13] offset:2336
	global_load_dword v88, v[104:105], off offset:1472
	global_load_dword v89, v[104:105], off offset:3520
	global_load_dword v90, v[104:105], off offset:1488
	global_load_dword v91, v[104:105], off offset:1504
	global_load_dword v92, v[104:105], off offset:1520
	global_load_dword v93, v[104:105], off offset:3536
	global_load_dword v94, v[104:105], off offset:3552
	global_load_dword v95, v[104:105], off offset:3568
	s_waitcnt vmcnt(32)
	v_mov_b32_e32 v12, v96
	v_mov_b32_e32 v1, v97
	v_mov_b32_e32 v11, v98
	v_mov_b32_e32 v13, v99
	v_mov_b32_e32 v14, v100
	v_mov_b32_e32 v10, v101
	v_mov_b32_e32 v15, v102
	v_mov_b32_e32 v16, v103
	v_add_f32_e32 v2, v0, v1
	v_max_f32_e32 v1, v12, v12
	v_max_f32_e32 v1, v2, v1
	v_max_f32_e32 v3, v11, v11
	v_sub_f32_e32 v2, v2, v1
	v_sub_f32_e32 v6, v12, v1
	v_add_f32_e32 v9, v1, v10
	v_mul_f32_e32 v10, 0x3fb8aa3b, v2
	v_mul_f32_e32 v12, 0x3fb8aa3b, v6
	v_max_f32_e32 v2, v9, v3
	v_max_f32_e32 v7, v13, v13
	v_exp_f32_e32 v6, v10
	v_exp_f32_e32 v10, v12
	v_sub_f32_e32 v3, v9, v2
	v_sub_f32_e32 v9, v11, v2
	v_add_f32_e32 v12, v2, v15
	v_mul_f32_e32 v11, 0x3fb8aa3b, v3
	v_mul_f32_e32 v9, 0x3fb8aa3b, v9
	v_max_f32_e32 v3, v12, v7
	v_max_f32_e32 v8, v14, v14
	v_exp_f32_e32 v7, v11
	v_exp_f32_e32 v11, v9
	v_sub_f32_e32 v9, v12, v3
	v_sub_f32_e32 v12, v13, v3
	v_add_f32_e32 v13, v3, v16
	v_mul_f32_e32 v9, 0x3fb8aa3b, v9
	v_max_f32_e32 v15, v13, v8
	v_exp_f32_e32 v8, v9
	v_sub_f32_e32 v9, v13, v15
	v_sub_f32_e32 v13, v14, v15
	v_mul_f32_e32 v9, 0x3fb8aa3b, v9
	v_mul_f32_e32 v12, 0x3fb8aa3b, v12
	v_mul_f32_e32 v13, 0x3fb8aa3b, v13
	v_exp_f32_e32 v9, v9
	v_exp_f32_e32 v12, v12
	v_exp_f32_e32 v13, v13
	ds_write_b128 v5, v[0:3] offset:4400
	v_mov_b32_e32 v0, v15
	ds_write_b128 v5, v[6:9] offset:304
	ds_write_b128 v5, v[10:13] offset:2352
	global_load_dword v96, v[104:105], off offset:1536
	global_load_dword v97, v[104:105], off offset:3584
	global_load_dword v98, v[104:105], off offset:1552
	global_load_dword v99, v[104:105], off offset:1568
	global_load_dword v100, v[104:105], off offset:1584
	global_load_dword v101, v[104:105], off offset:3600
	global_load_dword v102, v[104:105], off offset:3616
	global_load_dword v103, v[104:105], off offset:3632
	s_waitcnt vmcnt(32)
	v_mov_b32_e32 v12, v64
	v_mov_b32_e32 v1, v65
	v_mov_b32_e32 v11, v66
	v_mov_b32_e32 v13, v67
	v_mov_b32_e32 v14, v68
	v_mov_b32_e32 v10, v69
	v_mov_b32_e32 v15, v70
	v_mov_b32_e32 v16, v71
	v_add_f32_e32 v2, v0, v1
	v_max_f32_e32 v1, v12, v12
	v_max_f32_e32 v1, v2, v1
	v_max_f32_e32 v3, v11, v11
	v_sub_f32_e32 v2, v2, v1
	v_sub_f32_e32 v6, v12, v1
	v_add_f32_e32 v9, v1, v10
	v_mul_f32_e32 v10, 0x3fb8aa3b, v2
	v_mul_f32_e32 v12, 0x3fb8aa3b, v6
	v_max_f32_e32 v2, v9, v3
	v_max_f32_e32 v7, v13, v13
	v_exp_f32_e32 v6, v10
	v_exp_f32_e32 v10, v12
	v_sub_f32_e32 v3, v9, v2
	v_sub_f32_e32 v9, v11, v2
	v_add_f32_e32 v12, v2, v15
	v_mul_f32_e32 v11, 0x3fb8aa3b, v3
	v_mul_f32_e32 v9, 0x3fb8aa3b, v9
	v_max_f32_e32 v3, v12, v7
	v_max_f32_e32 v8, v14, v14
	v_exp_f32_e32 v7, v11
	v_exp_f32_e32 v11, v9
	v_sub_f32_e32 v9, v12, v3
	v_sub_f32_e32 v12, v13, v3
	v_add_f32_e32 v13, v3, v16
	v_mul_f32_e32 v9, 0x3fb8aa3b, v9
	v_max_f32_e32 v15, v13, v8
	v_exp_f32_e32 v8, v9
	v_sub_f32_e32 v9, v13, v15
	v_sub_f32_e32 v13, v14, v15
	v_mul_f32_e32 v9, 0x3fb8aa3b, v9
	v_mul_f32_e32 v12, 0x3fb8aa3b, v12
	v_mul_f32_e32 v13, 0x3fb8aa3b, v13
	v_exp_f32_e32 v9, v9
	v_exp_f32_e32 v12, v12
	v_exp_f32_e32 v13, v13
	ds_write_b128 v5, v[0:3] offset:4416
	v_mov_b32_e32 v0, v15
	ds_write_b128 v5, v[6:9] offset:320
	ds_write_b128 v5, v[10:13] offset:2368
	global_load_dword v64, v[104:105], off offset:1600
	global_load_dword v65, v[104:105], off offset:3648
	global_load_dword v66, v[104:105], off offset:1616
	global_load_dword v67, v[104:105], off offset:1632
	global_load_dword v68, v[104:105], off offset:1648
	global_load_dword v69, v[104:105], off offset:3664
	global_load_dword v70, v[104:105], off offset:3680
	global_load_dword v71, v[104:105], off offset:3696
	s_waitcnt vmcnt(32)
	v_mov_b32_e32 v12, v72
	v_mov_b32_e32 v1, v73
	v_mov_b32_e32 v11, v74
	v_mov_b32_e32 v13, v75
	v_mov_b32_e32 v14, v76
	v_mov_b32_e32 v10, v77
	v_mov_b32_e32 v15, v78
	v_mov_b32_e32 v16, v79
	v_add_f32_e32 v2, v0, v1
	v_max_f32_e32 v1, v12, v12
	v_max_f32_e32 v1, v2, v1
	v_max_f32_e32 v3, v11, v11
	v_sub_f32_e32 v2, v2, v1
	v_sub_f32_e32 v6, v12, v1
	v_add_f32_e32 v9, v1, v10
	v_mul_f32_e32 v10, 0x3fb8aa3b, v2
	v_mul_f32_e32 v12, 0x3fb8aa3b, v6
	v_max_f32_e32 v2, v9, v3
	v_max_f32_e32 v7, v13, v13
	v_exp_f32_e32 v6, v10
	v_exp_f32_e32 v10, v12
	v_sub_f32_e32 v3, v9, v2
	v_sub_f32_e32 v9, v11, v2
	v_add_f32_e32 v12, v2, v15
	v_mul_f32_e32 v11, 0x3fb8aa3b, v3
	v_mul_f32_e32 v9, 0x3fb8aa3b, v9
	v_max_f32_e32 v3, v12, v7
	v_max_f32_e32 v8, v14, v14
	v_exp_f32_e32 v7, v11
	v_exp_f32_e32 v11, v9
	v_sub_f32_e32 v9, v12, v3
	v_sub_f32_e32 v12, v13, v3
	v_add_f32_e32 v13, v3, v16
	v_mul_f32_e32 v9, 0x3fb8aa3b, v9
	v_max_f32_e32 v15, v13, v8
	v_exp_f32_e32 v8, v9
	v_sub_f32_e32 v9, v13, v15
	v_sub_f32_e32 v13, v14, v15
	v_mul_f32_e32 v9, 0x3fb8aa3b, v9
	v_mul_f32_e32 v12, 0x3fb8aa3b, v12
	v_mul_f32_e32 v13, 0x3fb8aa3b, v13
	v_exp_f32_e32 v9, v9
	v_exp_f32_e32 v12, v12
	v_exp_f32_e32 v13, v13
	ds_write_b128 v5, v[0:3] offset:4432
	v_mov_b32_e32 v0, v15
	ds_write_b128 v5, v[6:9] offset:336
	ds_write_b128 v5, v[10:13] offset:2384
	global_load_dword v72, v[104:105], off offset:1664
	global_load_dword v73, v[104:105], off offset:3712
	global_load_dword v74, v[104:105], off offset:1680
	global_load_dword v75, v[104:105], off offset:1696
	global_load_dword v76, v[104:105], off offset:1712
	global_load_dword v77, v[104:105], off offset:3728
	global_load_dword v78, v[104:105], off offset:3744
	global_load_dword v79, v[104:105], off offset:3760
	s_waitcnt vmcnt(32)
	v_mov_b32_e32 v12, v80
	v_mov_b32_e32 v1, v81
	v_mov_b32_e32 v11, v82
	v_mov_b32_e32 v13, v83
	v_mov_b32_e32 v14, v84
	v_mov_b32_e32 v10, v85
	v_mov_b32_e32 v15, v86
	v_mov_b32_e32 v16, v87
	v_add_f32_e32 v2, v0, v1
	v_max_f32_e32 v1, v12, v12
	v_max_f32_e32 v1, v2, v1
	v_max_f32_e32 v3, v11, v11
	v_sub_f32_e32 v2, v2, v1
	v_sub_f32_e32 v6, v12, v1
	v_add_f32_e32 v9, v1, v10
	v_mul_f32_e32 v10, 0x3fb8aa3b, v2
	v_mul_f32_e32 v12, 0x3fb8aa3b, v6
	v_max_f32_e32 v2, v9, v3
	v_max_f32_e32 v7, v13, v13
	v_exp_f32_e32 v6, v10
	v_exp_f32_e32 v10, v12
	v_sub_f32_e32 v3, v9, v2
	v_sub_f32_e32 v9, v11, v2
	v_add_f32_e32 v12, v2, v15
	v_mul_f32_e32 v11, 0x3fb8aa3b, v3
	v_mul_f32_e32 v9, 0x3fb8aa3b, v9
	v_max_f32_e32 v3, v12, v7
	v_max_f32_e32 v8, v14, v14
	v_exp_f32_e32 v7, v11
	v_exp_f32_e32 v11, v9
	v_sub_f32_e32 v9, v12, v3
	v_sub_f32_e32 v12, v13, v3
	v_add_f32_e32 v13, v3, v16
	v_mul_f32_e32 v9, 0x3fb8aa3b, v9
	v_max_f32_e32 v15, v13, v8
	v_exp_f32_e32 v8, v9
	v_sub_f32_e32 v9, v13, v15
	v_sub_f32_e32 v13, v14, v15
	v_mul_f32_e32 v9, 0x3fb8aa3b, v9
	v_mul_f32_e32 v12, 0x3fb8aa3b, v12
	v_mul_f32_e32 v13, 0x3fb8aa3b, v13
	v_exp_f32_e32 v9, v9
	v_exp_f32_e32 v12, v12
	v_exp_f32_e32 v13, v13
	ds_write_b128 v5, v[0:3] offset:4448
	v_mov_b32_e32 v0, v15
	ds_write_b128 v5, v[6:9] offset:352
	ds_write_b128 v5, v[10:13] offset:2400
	global_load_dword v80, v[104:105], off offset:1728
	global_load_dword v81, v[104:105], off offset:3776
	global_load_dword v82, v[104:105], off offset:1744
	global_load_dword v83, v[104:105], off offset:1760
	global_load_dword v84, v[104:105], off offset:1776
	global_load_dword v85, v[104:105], off offset:3792
	global_load_dword v86, v[104:105], off offset:3808
	global_load_dword v87, v[104:105], off offset:3824
	s_waitcnt vmcnt(32)
	v_mov_b32_e32 v12, v88
	v_mov_b32_e32 v1, v89
	v_mov_b32_e32 v11, v90
	v_mov_b32_e32 v13, v91
	v_mov_b32_e32 v14, v92
	v_mov_b32_e32 v10, v93
	v_mov_b32_e32 v15, v94
	v_mov_b32_e32 v16, v95
	v_add_f32_e32 v2, v0, v1
	v_max_f32_e32 v1, v12, v12
	v_max_f32_e32 v1, v2, v1
	v_max_f32_e32 v3, v11, v11
	v_sub_f32_e32 v2, v2, v1
	v_sub_f32_e32 v6, v12, v1
	v_add_f32_e32 v9, v1, v10
	v_mul_f32_e32 v10, 0x3fb8aa3b, v2
	v_mul_f32_e32 v12, 0x3fb8aa3b, v6
	v_max_f32_e32 v2, v9, v3
	v_max_f32_e32 v7, v13, v13
	v_exp_f32_e32 v6, v10
	v_exp_f32_e32 v10, v12
	v_sub_f32_e32 v3, v9, v2
	v_sub_f32_e32 v9, v11, v2
	v_add_f32_e32 v12, v2, v15
	v_mul_f32_e32 v11, 0x3fb8aa3b, v3
	v_mul_f32_e32 v9, 0x3fb8aa3b, v9
	v_max_f32_e32 v3, v12, v7
	v_max_f32_e32 v8, v14, v14
	v_exp_f32_e32 v7, v11
	v_exp_f32_e32 v11, v9
	v_sub_f32_e32 v9, v12, v3
	v_sub_f32_e32 v12, v13, v3
	v_add_f32_e32 v13, v3, v16
	v_mul_f32_e32 v9, 0x3fb8aa3b, v9
	v_max_f32_e32 v15, v13, v8
	v_exp_f32_e32 v8, v9
	v_sub_f32_e32 v9, v13, v15
	v_sub_f32_e32 v13, v14, v15
	v_mul_f32_e32 v9, 0x3fb8aa3b, v9
	v_mul_f32_e32 v12, 0x3fb8aa3b, v12
	v_mul_f32_e32 v13, 0x3fb8aa3b, v13
	v_exp_f32_e32 v9, v9
	v_exp_f32_e32 v12, v12
	v_exp_f32_e32 v13, v13
	ds_write_b128 v5, v[0:3] offset:4464
	v_mov_b32_e32 v0, v15
	ds_write_b128 v5, v[6:9] offset:368
	ds_write_b128 v5, v[10:13] offset:2416
	global_load_dword v88, v[104:105], off offset:1792
	global_load_dword v89, v[104:105], off offset:3840
	global_load_dword v90, v[104:105], off offset:1808
	global_load_dword v91, v[104:105], off offset:1824
	global_load_dword v92, v[104:105], off offset:1840
	global_load_dword v93, v[104:105], off offset:3856
	global_load_dword v94, v[104:105], off offset:3872
	global_load_dword v95, v[104:105], off offset:3888
	s_waitcnt vmcnt(32)
	v_mov_b32_e32 v12, v96
	v_mov_b32_e32 v1, v97
	v_mov_b32_e32 v11, v98
	v_mov_b32_e32 v13, v99
	v_mov_b32_e32 v14, v100
	v_mov_b32_e32 v10, v101
	v_mov_b32_e32 v15, v102
	v_mov_b32_e32 v16, v103
	v_add_f32_e32 v2, v0, v1
	v_max_f32_e32 v1, v12, v12
	v_max_f32_e32 v1, v2, v1
	v_max_f32_e32 v3, v11, v11
	v_sub_f32_e32 v2, v2, v1
	v_sub_f32_e32 v6, v12, v1
	v_add_f32_e32 v9, v1, v10
	v_mul_f32_e32 v10, 0x3fb8aa3b, v2
	v_mul_f32_e32 v12, 0x3fb8aa3b, v6
	v_max_f32_e32 v2, v9, v3
	v_max_f32_e32 v7, v13, v13
	v_exp_f32_e32 v6, v10
	v_exp_f32_e32 v10, v12
	v_sub_f32_e32 v3, v9, v2
	v_sub_f32_e32 v9, v11, v2
	v_add_f32_e32 v12, v2, v15
	v_mul_f32_e32 v11, 0x3fb8aa3b, v3
	v_mul_f32_e32 v9, 0x3fb8aa3b, v9
	v_max_f32_e32 v3, v12, v7
	v_max_f32_e32 v8, v14, v14
	v_exp_f32_e32 v7, v11
	v_exp_f32_e32 v11, v9
	v_sub_f32_e32 v9, v12, v3
	v_sub_f32_e32 v12, v13, v3
	v_add_f32_e32 v13, v3, v16
	v_mul_f32_e32 v9, 0x3fb8aa3b, v9
	v_max_f32_e32 v15, v13, v8
	v_exp_f32_e32 v8, v9
	v_sub_f32_e32 v9, v13, v15
	v_sub_f32_e32 v13, v14, v15
	v_mul_f32_e32 v9, 0x3fb8aa3b, v9
	v_mul_f32_e32 v12, 0x3fb8aa3b, v12
	v_mul_f32_e32 v13, 0x3fb8aa3b, v13
	v_exp_f32_e32 v9, v9
	v_exp_f32_e32 v12, v12
	v_exp_f32_e32 v13, v13
	ds_write_b128 v5, v[0:3] offset:4480
	v_mov_b32_e32 v0, v15
	ds_write_b128 v5, v[6:9] offset:384
	ds_write_b128 v5, v[10:13] offset:2432
	global_load_dword v96, v[104:105], off offset:1856
	global_load_dword v97, v[104:105], off offset:3904
	global_load_dword v98, v[104:105], off offset:1872
	global_load_dword v99, v[104:105], off offset:1888
	global_load_dword v100, v[104:105], off offset:1904
	global_load_dword v101, v[104:105], off offset:3920
	global_load_dword v102, v[104:105], off offset:3936
	global_load_dword v103, v[104:105], off offset:3952
	s_waitcnt vmcnt(32)
	v_mov_b32_e32 v12, v64
	v_mov_b32_e32 v1, v65
	v_mov_b32_e32 v11, v66
	v_mov_b32_e32 v13, v67
	v_mov_b32_e32 v14, v68
	v_mov_b32_e32 v10, v69
	v_mov_b32_e32 v15, v70
	v_mov_b32_e32 v16, v71
	v_add_f32_e32 v2, v0, v1
	v_max_f32_e32 v1, v12, v12
	v_max_f32_e32 v1, v2, v1
	v_max_f32_e32 v3, v11, v11
	v_sub_f32_e32 v2, v2, v1
	v_sub_f32_e32 v6, v12, v1
	v_add_f32_e32 v9, v1, v10
	v_mul_f32_e32 v10, 0x3fb8aa3b, v2
	v_mul_f32_e32 v12, 0x3fb8aa3b, v6
	v_max_f32_e32 v2, v9, v3
	v_max_f32_e32 v7, v13, v13
	v_exp_f32_e32 v6, v10
	v_exp_f32_e32 v10, v12
	v_sub_f32_e32 v3, v9, v2
	v_sub_f32_e32 v9, v11, v2
	v_add_f32_e32 v12, v2, v15
	v_mul_f32_e32 v11, 0x3fb8aa3b, v3
	v_mul_f32_e32 v9, 0x3fb8aa3b, v9
	v_max_f32_e32 v3, v12, v7
	v_max_f32_e32 v8, v14, v14
	v_exp_f32_e32 v7, v11
	v_exp_f32_e32 v11, v9
	v_sub_f32_e32 v9, v12, v3
	v_sub_f32_e32 v12, v13, v3
	v_add_f32_e32 v13, v3, v16
	v_mul_f32_e32 v9, 0x3fb8aa3b, v9
	v_max_f32_e32 v15, v13, v8
	v_exp_f32_e32 v8, v9
	v_sub_f32_e32 v9, v13, v15
	v_sub_f32_e32 v13, v14, v15
	v_mul_f32_e32 v9, 0x3fb8aa3b, v9
	v_mul_f32_e32 v12, 0x3fb8aa3b, v12
	v_mul_f32_e32 v13, 0x3fb8aa3b, v13
	v_exp_f32_e32 v9, v9
	v_exp_f32_e32 v12, v12
	v_exp_f32_e32 v13, v13
	ds_write_b128 v5, v[0:3] offset:4496
	v_mov_b32_e32 v0, v15
	ds_write_b128 v5, v[6:9] offset:400
	ds_write_b128 v5, v[10:13] offset:2448
	global_load_dword v64, v[104:105], off offset:1920
	global_load_dword v65, v[104:105], off offset:3968
	global_load_dword v66, v[104:105], off offset:1936
	global_load_dword v67, v[104:105], off offset:1952
	global_load_dword v68, v[104:105], off offset:1968
	global_load_dword v69, v[104:105], off offset:3984
	global_load_dword v70, v[104:105], off offset:4000
	global_load_dword v71, v[104:105], off offset:4016
	s_waitcnt vmcnt(32)
	v_mov_b32_e32 v12, v72
	v_mov_b32_e32 v1, v73
	v_mov_b32_e32 v11, v74
	v_mov_b32_e32 v13, v75
	v_mov_b32_e32 v14, v76
	v_mov_b32_e32 v10, v77
	v_mov_b32_e32 v15, v78
	v_mov_b32_e32 v16, v79
	v_add_f32_e32 v2, v0, v1
	v_max_f32_e32 v1, v12, v12
	v_max_f32_e32 v1, v2, v1
	v_max_f32_e32 v3, v11, v11
	v_sub_f32_e32 v2, v2, v1
	v_sub_f32_e32 v6, v12, v1
	v_add_f32_e32 v9, v1, v10
	v_mul_f32_e32 v10, 0x3fb8aa3b, v2
	v_mul_f32_e32 v12, 0x3fb8aa3b, v6
	v_max_f32_e32 v2, v9, v3
	v_max_f32_e32 v7, v13, v13
	v_exp_f32_e32 v6, v10
	v_exp_f32_e32 v10, v12
	v_sub_f32_e32 v3, v9, v2
	v_sub_f32_e32 v9, v11, v2
	v_add_f32_e32 v12, v2, v15
	v_mul_f32_e32 v11, 0x3fb8aa3b, v3
	v_mul_f32_e32 v9, 0x3fb8aa3b, v9
	v_max_f32_e32 v3, v12, v7
	v_max_f32_e32 v8, v14, v14
	v_exp_f32_e32 v7, v11
	v_exp_f32_e32 v11, v9
	v_sub_f32_e32 v9, v12, v3
	v_sub_f32_e32 v12, v13, v3
	v_add_f32_e32 v13, v3, v16
	v_mul_f32_e32 v9, 0x3fb8aa3b, v9
	v_max_f32_e32 v15, v13, v8
	v_exp_f32_e32 v8, v9
	v_sub_f32_e32 v9, v13, v15
	v_sub_f32_e32 v13, v14, v15
	v_mul_f32_e32 v9, 0x3fb8aa3b, v9
	v_mul_f32_e32 v12, 0x3fb8aa3b, v12
	v_mul_f32_e32 v13, 0x3fb8aa3b, v13
	v_exp_f32_e32 v9, v9
	v_exp_f32_e32 v12, v12
	v_exp_f32_e32 v13, v13
	ds_write_b128 v5, v[0:3] offset:4512
	v_mov_b32_e32 v0, v15
	ds_write_b128 v5, v[6:9] offset:416
	ds_write_b128 v5, v[10:13] offset:2464
	global_load_dword v72, v[104:105], off offset:1984
	global_load_dword v73, v[104:105], off offset:4032
	global_load_dword v74, v[104:105], off offset:2000
	global_load_dword v75, v[104:105], off offset:2016
	global_load_dword v76, v[104:105], off offset:2032
	global_load_dword v77, v[104:105], off offset:4048
	global_load_dword v78, v[104:105], off offset:4064
	global_load_dword v79, v[104:105], off offset:4080
	s_waitcnt vmcnt(32)
	v_mov_b32_e32 v12, v80
	v_mov_b32_e32 v1, v81
	v_mov_b32_e32 v11, v82
	v_mov_b32_e32 v13, v83
	v_mov_b32_e32 v14, v84
	v_mov_b32_e32 v10, v85
	v_mov_b32_e32 v15, v86
	v_mov_b32_e32 v16, v87
	v_add_f32_e32 v2, v0, v1
	v_max_f32_e32 v1, v12, v12
	v_max_f32_e32 v1, v2, v1
	v_max_f32_e32 v3, v11, v11
	v_sub_f32_e32 v2, v2, v1
	v_sub_f32_e32 v6, v12, v1
	v_add_f32_e32 v9, v1, v10
	v_mul_f32_e32 v10, 0x3fb8aa3b, v2
	v_mul_f32_e32 v12, 0x3fb8aa3b, v6
	v_max_f32_e32 v2, v9, v3
	v_max_f32_e32 v7, v13, v13
	v_exp_f32_e32 v6, v10
	v_exp_f32_e32 v10, v12
	v_sub_f32_e32 v3, v9, v2
	v_sub_f32_e32 v9, v11, v2
	v_add_f32_e32 v12, v2, v15
	v_mul_f32_e32 v11, 0x3fb8aa3b, v3
	v_mul_f32_e32 v9, 0x3fb8aa3b, v9
	v_max_f32_e32 v3, v12, v7
	v_max_f32_e32 v8, v14, v14
	v_exp_f32_e32 v7, v11
	v_exp_f32_e32 v11, v9
	v_sub_f32_e32 v9, v12, v3
	v_sub_f32_e32 v12, v13, v3
	v_add_f32_e32 v13, v3, v16
	v_mul_f32_e32 v9, 0x3fb8aa3b, v9
	v_max_f32_e32 v15, v13, v8
	v_exp_f32_e32 v8, v9
	v_sub_f32_e32 v9, v13, v15
	v_sub_f32_e32 v13, v14, v15
	v_mul_f32_e32 v9, 0x3fb8aa3b, v9
	v_mul_f32_e32 v12, 0x3fb8aa3b, v12
	v_mul_f32_e32 v13, 0x3fb8aa3b, v13
	v_exp_f32_e32 v9, v9
	v_exp_f32_e32 v12, v12
	v_exp_f32_e32 v13, v13
	ds_write_b128 v5, v[0:3] offset:4528
	v_mov_b32_e32 v0, v15
	ds_write_b128 v5, v[6:9] offset:432
	ds_write_b128 v5, v[10:13] offset:2480
	s_waitcnt vmcnt(24)
	v_mov_b32_e32 v12, v88
	v_mov_b32_e32 v1, v89
	v_mov_b32_e32 v11, v90
	v_mov_b32_e32 v13, v91
	v_mov_b32_e32 v14, v92
	v_mov_b32_e32 v10, v93
	v_mov_b32_e32 v15, v94
	v_mov_b32_e32 v16, v95
	v_add_f32_e32 v2, v0, v1
	v_max_f32_e32 v1, v12, v12
	v_max_f32_e32 v1, v2, v1
	v_max_f32_e32 v3, v11, v11
	v_sub_f32_e32 v2, v2, v1
	v_sub_f32_e32 v6, v12, v1
	v_add_f32_e32 v9, v1, v10
	v_mul_f32_e32 v10, 0x3fb8aa3b, v2
	v_mul_f32_e32 v12, 0x3fb8aa3b, v6
	v_max_f32_e32 v2, v9, v3
	v_max_f32_e32 v7, v13, v13
	v_exp_f32_e32 v6, v10
	v_exp_f32_e32 v10, v12
	v_sub_f32_e32 v3, v9, v2
	v_sub_f32_e32 v9, v11, v2
	v_add_f32_e32 v12, v2, v15
	v_mul_f32_e32 v11, 0x3fb8aa3b, v3
	v_mul_f32_e32 v9, 0x3fb8aa3b, v9
	v_max_f32_e32 v3, v12, v7
	v_max_f32_e32 v8, v14, v14
	v_exp_f32_e32 v7, v11
	v_exp_f32_e32 v11, v9
	v_sub_f32_e32 v9, v12, v3
	v_sub_f32_e32 v12, v13, v3
	v_add_f32_e32 v13, v3, v16
	v_mul_f32_e32 v9, 0x3fb8aa3b, v9
	v_max_f32_e32 v15, v13, v8
	v_exp_f32_e32 v8, v9
	v_sub_f32_e32 v9, v13, v15
	v_sub_f32_e32 v13, v14, v15
	v_mul_f32_e32 v9, 0x3fb8aa3b, v9
	v_mul_f32_e32 v12, 0x3fb8aa3b, v12
	v_mul_f32_e32 v13, 0x3fb8aa3b, v13
	v_exp_f32_e32 v9, v9
	v_exp_f32_e32 v12, v12
	v_exp_f32_e32 v13, v13
	ds_write_b128 v5, v[0:3] offset:4544
	v_mov_b32_e32 v0, v15
	ds_write_b128 v5, v[6:9] offset:448
	ds_write_b128 v5, v[10:13] offset:2496
	s_waitcnt vmcnt(16)
	v_mov_b32_e32 v12, v96
	v_mov_b32_e32 v1, v97
	v_mov_b32_e32 v11, v98
	v_mov_b32_e32 v13, v99
	v_mov_b32_e32 v14, v100
	v_mov_b32_e32 v10, v101
	v_mov_b32_e32 v15, v102
	v_mov_b32_e32 v16, v103
	v_add_f32_e32 v2, v0, v1
	v_max_f32_e32 v1, v12, v12
	v_max_f32_e32 v1, v2, v1
	v_max_f32_e32 v3, v11, v11
	v_sub_f32_e32 v2, v2, v1
	v_sub_f32_e32 v6, v12, v1
	v_add_f32_e32 v9, v1, v10
	v_mul_f32_e32 v10, 0x3fb8aa3b, v2
	v_mul_f32_e32 v12, 0x3fb8aa3b, v6
	v_max_f32_e32 v2, v9, v3
	v_max_f32_e32 v7, v13, v13
	v_exp_f32_e32 v6, v10
	v_exp_f32_e32 v10, v12
	v_sub_f32_e32 v3, v9, v2
	v_sub_f32_e32 v9, v11, v2
	v_add_f32_e32 v12, v2, v15
	v_mul_f32_e32 v11, 0x3fb8aa3b, v3
	v_mul_f32_e32 v9, 0x3fb8aa3b, v9
	v_max_f32_e32 v3, v12, v7
	v_max_f32_e32 v8, v14, v14
	v_exp_f32_e32 v7, v11
	v_exp_f32_e32 v11, v9
	v_sub_f32_e32 v9, v12, v3
	v_sub_f32_e32 v12, v13, v3
	v_add_f32_e32 v13, v3, v16
	v_mul_f32_e32 v9, 0x3fb8aa3b, v9
	v_max_f32_e32 v15, v13, v8
	v_exp_f32_e32 v8, v9
	v_sub_f32_e32 v9, v13, v15
	v_sub_f32_e32 v13, v14, v15
	v_mul_f32_e32 v9, 0x3fb8aa3b, v9
	v_mul_f32_e32 v12, 0x3fb8aa3b, v12
	v_mul_f32_e32 v13, 0x3fb8aa3b, v13
	v_exp_f32_e32 v9, v9
	v_exp_f32_e32 v12, v12
	v_exp_f32_e32 v13, v13
	ds_write_b128 v5, v[0:3] offset:4560
	v_mov_b32_e32 v0, v15
	ds_write_b128 v5, v[6:9] offset:464
	ds_write_b128 v5, v[10:13] offset:2512
	s_waitcnt vmcnt(8)
	v_mov_b32_e32 v12, v64
	v_mov_b32_e32 v1, v65
	v_mov_b32_e32 v11, v66
	v_mov_b32_e32 v13, v67
	v_mov_b32_e32 v14, v68
	v_mov_b32_e32 v10, v69
	v_mov_b32_e32 v15, v70
	v_mov_b32_e32 v16, v71
	v_add_f32_e32 v2, v0, v1
	v_max_f32_e32 v1, v12, v12
	v_max_f32_e32 v1, v2, v1
	v_max_f32_e32 v3, v11, v11
	v_sub_f32_e32 v2, v2, v1
	v_sub_f32_e32 v6, v12, v1
	v_add_f32_e32 v9, v1, v10
	v_mul_f32_e32 v10, 0x3fb8aa3b, v2
	v_mul_f32_e32 v12, 0x3fb8aa3b, v6
	v_max_f32_e32 v2, v9, v3
	v_max_f32_e32 v7, v13, v13
	v_exp_f32_e32 v6, v10
	v_exp_f32_e32 v10, v12
	v_sub_f32_e32 v3, v9, v2
	v_sub_f32_e32 v9, v11, v2
	v_add_f32_e32 v12, v2, v15
	v_mul_f32_e32 v11, 0x3fb8aa3b, v3
	v_mul_f32_e32 v9, 0x3fb8aa3b, v9
	v_max_f32_e32 v3, v12, v7
	v_max_f32_e32 v8, v14, v14
	v_exp_f32_e32 v7, v11
	v_exp_f32_e32 v11, v9
	v_sub_f32_e32 v9, v12, v3
	v_sub_f32_e32 v12, v13, v3
	v_add_f32_e32 v13, v3, v16
	v_mul_f32_e32 v9, 0x3fb8aa3b, v9
	v_max_f32_e32 v15, v13, v8
	v_exp_f32_e32 v8, v9
	v_sub_f32_e32 v9, v13, v15
	v_sub_f32_e32 v13, v14, v15
	v_mul_f32_e32 v9, 0x3fb8aa3b, v9
	v_mul_f32_e32 v12, 0x3fb8aa3b, v12
	v_mul_f32_e32 v13, 0x3fb8aa3b, v13
	v_exp_f32_e32 v9, v9
	v_exp_f32_e32 v12, v12
	v_exp_f32_e32 v13, v13
	ds_write_b128 v5, v[0:3] offset:4576
	v_mov_b32_e32 v0, v15
	ds_write_b128 v5, v[6:9] offset:480
	ds_write_b128 v5, v[10:13] offset:2528
	s_waitcnt vmcnt(0)
	v_mov_b32_e32 v12, v72
	v_mov_b32_e32 v1, v73
	v_mov_b32_e32 v11, v74
	v_mov_b32_e32 v13, v75
	v_mov_b32_e32 v14, v76
	v_mov_b32_e32 v10, v77
	v_mov_b32_e32 v15, v78
	v_mov_b32_e32 v16, v79
	v_add_f32_e32 v2, v0, v1
	v_max_f32_e32 v1, v12, v12
	v_max_f32_e32 v1, v2, v1
	v_max_f32_e32 v3, v11, v11
	v_sub_f32_e32 v2, v2, v1
	v_sub_f32_e32 v6, v12, v1
	v_add_f32_e32 v9, v1, v10
	v_mul_f32_e32 v10, 0x3fb8aa3b, v2
	v_mul_f32_e32 v12, 0x3fb8aa3b, v6
	v_max_f32_e32 v2, v9, v3
	v_max_f32_e32 v7, v13, v13
	v_exp_f32_e32 v6, v10
	v_exp_f32_e32 v10, v12
	v_sub_f32_e32 v3, v9, v2
	v_sub_f32_e32 v9, v11, v2
	v_add_f32_e32 v12, v2, v15
	v_mul_f32_e32 v11, 0x3fb8aa3b, v3
	v_mul_f32_e32 v9, 0x3fb8aa3b, v9
	v_max_f32_e32 v3, v12, v7
	v_max_f32_e32 v8, v14, v14
	v_exp_f32_e32 v7, v11
	v_exp_f32_e32 v11, v9
	v_sub_f32_e32 v9, v12, v3
	v_sub_f32_e32 v12, v13, v3
	v_add_f32_e32 v13, v3, v16
	v_mul_f32_e32 v9, 0x3fb8aa3b, v9
	v_max_f32_e32 v15, v13, v8
	v_exp_f32_e32 v8, v9
	v_sub_f32_e32 v9, v13, v15
	v_sub_f32_e32 v13, v14, v15
	v_mul_f32_e32 v9, 0x3fb8aa3b, v9
	v_mul_f32_e32 v12, 0x3fb8aa3b, v12
	v_mul_f32_e32 v13, 0x3fb8aa3b, v13
	v_exp_f32_e32 v9, v9
	v_exp_f32_e32 v12, v12
	v_exp_f32_e32 v13, v13
	ds_write_b128 v5, v[0:3] offset:4592
	v_mov_b32_e32 v0, v15
	ds_write_b128 v5, v[6:9] offset:496
	ds_write_b128 v5, v[10:13] offset:2544
	s_movk_i32 s11, 0x200
